# mem_attn: the vmcnt wait guarding the Q fragments moved down to its first consumer (first MFMA), after the first LDS ring reads are issued
# speedup vs baseline: 1.0001x; 1.0001x over previous
; __device__ __forceinline__ void mem_attn_phase(int wv, const Args& A, LAS unsigned char* lds, int G) {
;     ...
;         h16x8 qf[4];
; #pragma unroll
;         for (int ks = 0; ks < 4; ++ks) qf[ks] = __builtin_bit_cast(h16x8, *(const u32x4*)(MQ + (row0 + fr) * 512 + h * 128 + ks * 32 + fq * 8));
;         f32x4 lg[16]; float m = -INFINITY;
; #pragma unroll
;         for (int kt = 0; kt < 16; ++kt) { f32x4 a = {0.f, 0.f, 0.f, 0.f};
; #pragma unroll
;             for (int ks = 0; ks < 4; ++ks) { const h16x8 kf = __builtin_bit_cast(h16x8, *(const u32x4*)(Kb + (size_t)(kt * 16 + fr) * 512 + h * 128 + ks * 32 + fq * 8)); a = __builtin_amdgcn_mfma_f32_16x16x32_f16(kf, qf[ks], a, 0, 0, 0); }
;             lg[kt] = a; m = fmaxf(m, fmaxf(fmaxf(a[0], a[1]), fmaxf(a[2], a[3]))); }
.Lma_staged:
	s_mov_b64 s[94:95], s[36:37]
	s_waitcnt lgkmcnt(0)
	s_barrier
	ds_read_b128 v[32:35], v7
	ds_read_b128 v[36:39], v7 offset:1024
	ds_read_b128 v[40:43], v7 offset:2048
	ds_read_b128 v[44:47], v7 offset:3072
	ds_read_b128 v[48:51], v7 offset:4096
	ds_read_b128 v[52:55], v7 offset:5120
	ds_read_b128 v[56:59], v7 offset:6144
	ds_read_b128 v[60:63], v7 offset:7168
	ds_read_b128 v[240:243], v7 offset:8192
	ds_read_b128 v[244:247], v7 offset:9216
	ds_read_b128 v[248:251], v7 offset:10240
	ds_read_b128 v[252:255], v7 offset:11264
	s_waitcnt lgkmcnt(11)
	s_waitcnt vmcnt(8)
	v_mfma_f32_16x16x32_f16 v[96:99], v[32:35], v[16:19], 0
	ds_read_b128 v[32:35], v7 offset:12288
	s_waitcnt lgkmcnt(11)
	v_mfma_f32_16x16x32_f16 v[96:99], v[36:39], v[20:23], v[96:99]
	ds_read_b128 v[36:39], v7 offset:13312
	s_waitcnt lgkmcnt(11)
	v_mfma_f32_16x16x32_f16 v[96:99], v[40:43], v[24:27], v[96:99]
	ds_read_b128 v[40:43], v7 offset:14336
	s_waitcnt lgkmcnt(11)
	v_mfma_f32_16x16x32_f16 v[96:99], v[44:47], v[28:31], v[96:99]
	ds_read_b128 v[44:47], v7 offset:15360
	s_waitcnt lgkmcnt(11)
	v_mfma_f32_16x16x32_f16 v[100:103], v[48:51], v[16:19], 0
	ds_read_b128 v[48:51], v7 offset:16384
	s_waitcnt lgkmcnt(11)
	v_mfma_f32_16x16x32_f16 v[100:103], v[52:55], v[20:23], v[100:103]
	ds_read_b128 v[52:55], v7 offset:17408
	s_waitcnt lgkmcnt(11)
	v_mfma_f32_16x16x32_f16 v[100:103], v[56:59], v[24:27], v[100:103]
	ds_read_b128 v[56:59], v7 offset:18432
	s_waitcnt lgkmcnt(11)
	v_mfma_f32_16x16x32_f16 v[100:103], v[60:63], v[28:31], v[100:103]
	ds_read_b128 v[60:63], v7 offset:19456
	s_waitcnt lgkmcnt(11)
	v_mfma_f32_16x16x32_f16 v[104:107], v[240:243], v[16:19], 0
	ds_read_b128 v[240:243], v7 offset:20480
	s_waitcnt lgkmcnt(11)
	v_mfma_f32_16x16x32_f16 v[104:107], v[244:247], v[20:23], v[104:107]
	ds_read_b128 v[244:247], v7 offset:21504
	s_waitcnt lgkmcnt(11)
	v_mfma_f32_16x16x32_f16 v[104:107], v[248:251], v[24:27], v[104:107]
	ds_read_b128 v[248:251], v7 offset:22528
	s_waitcnt lgkmcnt(11)
	v_mfma_f32_16x16x32_f16 v[104:107], v[252:255], v[28:31], v[104:107]
	ds_read_b128 v[252:255], v7 offset:23552
	s_waitcnt lgkmcnt(11)
	v_mfma_f32_16x16x32_f16 v[108:111], v[32:35], v[16:19], 0
	ds_read_b128 v[32:35], v7 offset:24576
	s_waitcnt lgkmcnt(11)
	v_mfma_f32_16x16x32_f16 v[108:111], v[36:39], v[20:23], v[108:111]
	ds_read_b128 v[36:39], v7 offset:25600
	s_waitcnt lgkmcnt(11)
	v_mfma_f32_16x16x32_f16 v[108:111], v[40:43], v[24:27], v[108:111]
	ds_read_b128 v[40:43], v7 offset:26624
	s_waitcnt lgkmcnt(11)
	v_mfma_f32_16x16x32_f16 v[108:111], v[44:47], v[28:31], v[108:111]
	ds_read_b128 v[44:47], v7 offset:27648
	s_waitcnt lgkmcnt(11)
	v_mfma_f32_16x16x32_f16 v[112:115], v[48:51], v[16:19], 0
	ds_read_b128 v[48:51], v7 offset:28672
	s_waitcnt lgkmcnt(11)
	v_mfma_f32_16x16x32_f16 v[112:115], v[52:55], v[20:23], v[112:115]
	ds_read_b128 v[52:55], v7 offset:29696
	s_waitcnt lgkmcnt(11)
	v_mfma_f32_16x16x32_f16 v[112:115], v[56:59], v[24:27], v[112:115]
	ds_read_b128 v[56:59], v7 offset:30720
	s_waitcnt lgkmcnt(11)
	v_mfma_f32_16x16x32_f16 v[112:115], v[60:63], v[28:31], v[112:115]
	ds_read_b128 v[60:63], v7 offset:31744
	s_waitcnt lgkmcnt(11)
	v_mfma_f32_16x16x32_f16 v[116:119], v[240:243], v[16:19], 0
	ds_read_b128 v[240:243], v7 offset:32768
	s_waitcnt lgkmcnt(11)
	v_mfma_f32_16x16x32_f16 v[116:119], v[244:247], v[20:23], v[116:119]
	ds_read_b128 v[244:247], v7 offset:33792
	s_waitcnt lgkmcnt(11)
	v_mfma_f32_16x16x32_f16 v[116:119], v[248:251], v[24:27], v[116:119]
	ds_read_b128 v[248:251], v7 offset:34816
	s_waitcnt lgkmcnt(11)
	v_mfma_f32_16x16x32_f16 v[116:119], v[252:255], v[28:31], v[116:119]
	ds_read_b128 v[252:255], v7 offset:35840
	s_waitcnt lgkmcnt(11)
	v_mfma_f32_16x16x32_f16 v[120:123], v[32:35], v[16:19], 0
	ds_read_b128 v[32:35], v7 offset:36864
	s_waitcnt lgkmcnt(11)
	v_mfma_f32_16x16x32_f16 v[120:123], v[36:39], v[20:23], v[120:123]
	ds_read_b128 v[36:39], v7 offset:37888
	s_waitcnt lgkmcnt(11)
	v_mfma_f32_16x16x32_f16 v[120:123], v[40:43], v[24:27], v[120:123]
	ds_read_b128 v[40:43], v7 offset:38912
	s_waitcnt lgkmcnt(11)
	v_mfma_f32_16x16x32_f16 v[120:123], v[44:47], v[28:31], v[120:123]
	ds_read_b128 v[44:47], v7 offset:39936
	s_waitcnt lgkmcnt(11)
	v_mfma_f32_16x16x32_f16 v[124:127], v[48:51], v[16:19], 0
	ds_read_b128 v[48:51], v7 offset:40960
	s_waitcnt lgkmcnt(11)
	v_mfma_f32_16x16x32_f16 v[124:127], v[52:55], v[20:23], v[124:127]
	ds_read_b128 v[52:55], v7 offset:41984
	s_waitcnt lgkmcnt(11)
	v_mfma_f32_16x16x32_f16 v[124:127], v[56:59], v[24:27], v[124:127]
	ds_read_b128 v[56:59], v7 offset:43008
	s_waitcnt lgkmcnt(11)
	v_mfma_f32_16x16x32_f16 v[124:127], v[60:63], v[28:31], v[124:127]
	ds_read_b128 v[60:63], v7 offset:44032
	s_waitcnt lgkmcnt(11)
	v_mfma_f32_16x16x32_f16 v[128:131], v[240:243], v[16:19], 0
	ds_read_b128 v[240:243], v7 offset:45056
	s_waitcnt lgkmcnt(11)
	v_mfma_f32_16x16x32_f16 v[128:131], v[244:247], v[20:23], v[128:131]
	ds_read_b128 v[244:247], v7 offset:46080
	s_waitcnt lgkmcnt(11)
	v_mfma_f32_16x16x32_f16 v[128:131], v[248:251], v[24:27], v[128:131]
	ds_read_b128 v[248:251], v7 offset:47104
	s_waitcnt lgkmcnt(11)
	v_mfma_f32_16x16x32_f16 v[128:131], v[252:255], v[28:31], v[128:131]
	ds_read_b128 v[252:255], v7 offset:48128
	s_waitcnt lgkmcnt(11)
	v_mfma_f32_16x16x32_f16 v[132:135], v[32:35], v[16:19], 0
	ds_read_b128 v[32:35], v7 offset:49152
	s_waitcnt lgkmcnt(11)
	v_mfma_f32_16x16x32_f16 v[132:135], v[36:39], v[20:23], v[132:135]
	ds_read_b128 v[36:39], v7 offset:50176
	s_waitcnt lgkmcnt(11)
	v_mfma_f32_16x16x32_f16 v[132:135], v[40:43], v[24:27], v[132:135]
	ds_read_b128 v[40:43], v7 offset:51200
	s_waitcnt lgkmcnt(11)
; #define LAS __attribute__((address_space(3)))
; __device__ __forceinline__ void mem_attn_phase(int wv, const Args& A, LAS unsigned char* lds, int G) {
;     ...
;         for (int kt = 0; kt < 16; ++kt) { f32x4 a = {0.f, 0.f, 0.f, 0.f};
; #pragma unroll
;             for (int ks = 0; ks < 4; ++ks) { const h16x8 kf = __builtin_bit_cast(h16x8, *(const u32x4*)(Kb + (size_t)(kt * 16 + fr) * 512 + h * 128 + ks * 32 + fq * 8)); a = __builtin_amdgcn_mfma_f32_16x16x32_f16(kf, qf[ks], a, 0, 0, 0); }
;             lg[kt] = a; m = fmaxf(m, fmaxf(fmaxf(a[0], a[1]), fmaxf(a[2], a[3]))); }
;         m = fmaxf(m, __shfl_xor(m, 16)); m = fmaxf(m, __shfl_xor(m, 32));
;         float sm = 0.f;
; #pragma unroll
;         for (int kt = 0; kt < 16; ++kt) { h16x4 p4;
; #pragma unroll
;             for (int r = 0; r < 4; ++r) { const float p = __expf(lg[kt][r] - m); sm += p; p4[r] = (h16)p; }
;             *(LAS u32x2*)(Pw + fr * 264 + kt * 16 + fq * 4) = __builtin_bit_cast(u32x2, p4); }
	v_mfma_f32_16x16x32_f16 v[132:135], v[44:47], v[28:31], v[132:135]
	ds_read_b128 v[44:47], v7 offset:52224
	s_waitcnt lgkmcnt(11)
	v_mfma_f32_16x16x32_f16 v[136:139], v[48:51], v[16:19], 0
	ds_read_b128 v[48:51], v7 offset:53248
	s_waitcnt lgkmcnt(11)
	v_mfma_f32_16x16x32_f16 v[136:139], v[52:55], v[20:23], v[136:139]
	ds_read_b128 v[52:55], v7 offset:54272
	s_waitcnt lgkmcnt(11)
	v_mfma_f32_16x16x32_f16 v[136:139], v[56:59], v[24:27], v[136:139]
	ds_read_b128 v[56:59], v7 offset:55296
	s_waitcnt lgkmcnt(11)
	v_mfma_f32_16x16x32_f16 v[136:139], v[60:63], v[28:31], v[136:139]
	ds_read_b128 v[60:63], v7 offset:56320
	s_waitcnt lgkmcnt(11)
	v_mfma_f32_16x16x32_f16 v[140:143], v[240:243], v[16:19], 0
	ds_read_b128 v[240:243], v7 offset:57344
	s_waitcnt lgkmcnt(11)
	v_mfma_f32_16x16x32_f16 v[140:143], v[244:247], v[20:23], v[140:143]
	ds_read_b128 v[244:247], v7 offset:58368
	s_waitcnt lgkmcnt(11)
	v_mfma_f32_16x16x32_f16 v[140:143], v[248:251], v[24:27], v[140:143]
	ds_read_b128 v[248:251], v7 offset:59392
	s_waitcnt lgkmcnt(11)
	v_mfma_f32_16x16x32_f16 v[140:143], v[252:255], v[28:31], v[140:143]
	ds_read_b128 v[252:255], v7 offset:60416
	s_waitcnt lgkmcnt(11)
	v_mfma_f32_16x16x32_f16 v[144:147], v[32:35], v[16:19], 0
	ds_read_b128 v[32:35], v7 offset:61440
	s_waitcnt lgkmcnt(11)
	v_mfma_f32_16x16x32_f16 v[144:147], v[36:39], v[20:23], v[144:147]
	ds_read_b128 v[36:39], v7 offset:62464
	s_waitcnt lgkmcnt(11)
	v_mfma_f32_16x16x32_f16 v[144:147], v[40:43], v[24:27], v[144:147]
	ds_read_b128 v[40:43], v7 offset:63488
	s_waitcnt lgkmcnt(11)
	v_mfma_f32_16x16x32_f16 v[144:147], v[44:47], v[28:31], v[144:147]
	ds_read_b128 v[44:47], v7 offset:64512
	s_waitcnt lgkmcnt(11)
	v_mfma_f32_16x16x32_f16 v[148:151], v[48:51], v[16:19], 0
	s_waitcnt lgkmcnt(10)
	v_mfma_f32_16x16x32_f16 v[148:151], v[52:55], v[20:23], v[148:151]
	s_waitcnt lgkmcnt(9)
	v_mfma_f32_16x16x32_f16 v[148:151], v[56:59], v[24:27], v[148:151]
	s_waitcnt lgkmcnt(8)
	v_mfma_f32_16x16x32_f16 v[148:151], v[60:63], v[28:31], v[148:151]
	s_waitcnt lgkmcnt(7)
	v_mfma_f32_16x16x32_f16 v[152:155], v[240:243], v[16:19], 0
	s_waitcnt lgkmcnt(6)
	v_mfma_f32_16x16x32_f16 v[152:155], v[244:247], v[20:23], v[152:155]
	s_waitcnt lgkmcnt(5)
	v_mfma_f32_16x16x32_f16 v[152:155], v[248:251], v[24:27], v[152:155]
	s_waitcnt lgkmcnt(4)
	v_mfma_f32_16x16x32_f16 v[152:155], v[252:255], v[28:31], v[152:155]
	s_waitcnt lgkmcnt(3)
	v_mfma_f32_16x16x32_f16 v[156:159], v[32:35], v[16:19], 0
	s_waitcnt lgkmcnt(2)
	v_mfma_f32_16x16x32_f16 v[156:159], v[36:39], v[20:23], v[156:159]
	s_waitcnt lgkmcnt(1)
	v_mfma_f32_16x16x32_f16 v[156:159], v[40:43], v[24:27], v[156:159]
	s_waitcnt lgkmcnt(0)
	v_mfma_f32_16x16x32_f16 v[156:159], v[44:47], v[28:31], v[156:159]
	s_nop 7
	s_nop 1
	v_max3_f32 v13, v96, v97, v98
	v_max3_f32 v13, v13, v99, v100
	v_max3_f32 v13, v13, v101, v102
	v_max3_f32 v13, v13, v103, v104
	v_max3_f32 v13, v13, v105, v106
	v_max3_f32 v13, v13, v107, v108
	v_max3_f32 v13, v13, v109, v110
	v_max3_f32 v13, v13, v111, v112
	v_max3_f32 v13, v13, v113, v114
	v_max3_f32 v13, v13, v115, v116
	v_max3_f32 v13, v13, v117, v118
	v_max3_f32 v13, v13, v119, v120
	v_max3_f32 v13, v13, v121, v122
	v_max3_f32 v13, v13, v123, v124
	v_max3_f32 v13, v13, v125, v126
	v_max3_f32 v13, v13, v127, v128
	v_max3_f32 v13, v13, v129, v130
	v_max3_f32 v13, v13, v131, v132
	v_max3_f32 v13, v13, v133, v134
	v_max3_f32 v13, v13, v135, v136
	v_max3_f32 v13, v13, v137, v138
	v_max3_f32 v13, v13, v139, v140
	v_max3_f32 v13, v13, v141, v142
	v_max3_f32 v13, v13, v143, v144
	v_max3_f32 v13, v13, v145, v146
	v_max3_f32 v13, v13, v147, v148
	v_max3_f32 v13, v13, v149, v150
	v_max3_f32 v13, v13, v151, v152
	v_max3_f32 v13, v13, v153, v154
	v_max3_f32 v13, v13, v155, v156
	v_max3_f32 v13, v13, v157, v158
	v_max_f32_e32 v13, v13, v159
	ds_bpermute_b32 v64, v11, v13
	s_waitcnt lgkmcnt(0)
	v_max_f32_e32 v13, v13, v64
	ds_bpermute_b32 v64, v12, v13
	s_waitcnt lgkmcnt(0)
	v_max_f32_e32 v13, v13, v64
	v_mov_b32_e32 v14, 0
	v_sub_f32_e32 v96, v96, v13
	v_sub_f32_e32 v97, v97, v13
	v_sub_f32_e32 v98, v98, v13
	v_sub_f32_e32 v99, v99, v13
	v_mul_f32_e32 v96, 0x3fb8aa3b, v96
	v_mul_f32_e32 v97, 0x3fb8aa3b, v97
	v_mul_f32_e32 v98, 0x3fb8aa3b, v98
	v_mul_f32_e32 v99, 0x3fb8aa3b, v99
	v_exp_f32_e32 v96, v96
	v_exp_f32_e32 v97, v97
	v_exp_f32_e32 v98, v98
	v_exp_f32_e32 v99, v99
	s_nop 0
	v_add_f32_e32 v14, v14, v96
	v_add_f32_e32 v14, v14, v97
	v_add_f32_e32 v14, v14, v98
	v_add_f32_e32 v14, v14, v99
	v_cvt_pk_f16_f32 v64, v96, v97
	v_cvt_pk_f16_f32 v65, v98, v99
	ds_write_b64 v8, v[64:65]
	v_sub_f32_e32 v100, v100, v13
	v_sub_f32_e32 v101, v101, v13
	v_sub_f32_e32 v102, v102, v13
	v_sub_f32_e32 v103, v103, v13
	v_mul_f32_e32 v100, 0x3fb8aa3b, v100
	v_mul_f32_e32 v101, 0x3fb8aa3b, v101
	v_mul_f32_e32 v102, 0x3fb8aa3b, v102
	v_mul_f32_e32 v103, 0x3fb8aa3b, v103
	v_exp_f32_e32 v100, v100
	v_exp_f32_e32 v101, v101
	v_exp_f32_e32 v102, v102
	v_exp_f32_e32 v103, v103
	s_nop 0
	v_add_f32_e32 v14, v14, v100
	v_add_f32_e32 v14, v14, v101
	v_add_f32_e32 v14, v14, v102
	v_add_f32_e32 v14, v14, v103
	v_cvt_pk_f16_f32 v66, v100, v101
	v_cvt_pk_f16_f32 v67, v102, v103
	ds_write_b64 v8, v[66:67] offset:32
	v_sub_f32_e32 v104, v104, v13
	v_sub_f32_e32 v105, v105, v13
	v_sub_f32_e32 v106, v106, v13
	v_sub_f32_e32 v107, v107, v13
	v_mul_f32_e32 v104, 0x3fb8aa3b, v104
	v_mul_f32_e32 v105, 0x3fb8aa3b, v105
	v_mul_f32_e32 v106, 0x3fb8aa3b, v106
	v_mul_f32_e32 v107, 0x3fb8aa3b, v107
	v_exp_f32_e32 v104, v104
	v_exp_f32_e32 v105, v105
	v_exp_f32_e32 v106, v106
	v_exp_f32_e32 v107, v107
	s_nop 0
	v_add_f32_e32 v14, v14, v104
	v_add_f32_e32 v14, v14, v105
	v_add_f32_e32 v14, v14, v106
; #define LAS __attribute__((address_space(3)))
; __device__ __forceinline__ void mem_attn_phase(int wv, const Args& A, LAS unsigned char* lds, int G) {
;     ...
;         for (int kt = 0; kt < 16; ++kt) { h16x4 p4;
; #pragma unroll
;             for (int r = 0; r < 4; ++r) { const float p = __expf(lg[kt][r] - m); sm += p; p4[r] = (h16)p; }
;             *(LAS u32x2*)(Pw + fr * 264 + kt * 16 + fq * 4) = __builtin_bit_cast(u32x2, p4); }
	v_add_f32_e32 v14, v14, v107
	v_cvt_pk_f16_f32 v64, v104, v105
	v_cvt_pk_f16_f32 v65, v106, v107
	ds_write_b64 v8, v[64:65] offset:64
	v_sub_f32_e32 v108, v108, v13
	v_sub_f32_e32 v109, v109, v13
	v_sub_f32_e32 v110, v110, v13
	v_sub_f32_e32 v111, v111, v13
	v_mul_f32_e32 v108, 0x3fb8aa3b, v108
	v_mul_f32_e32 v109, 0x3fb8aa3b, v109
	v_mul_f32_e32 v110, 0x3fb8aa3b, v110
	v_mul_f32_e32 v111, 0x3fb8aa3b, v111
	v_exp_f32_e32 v108, v108
	v_exp_f32_e32 v109, v109
	v_exp_f32_e32 v110, v110
	v_exp_f32_e32 v111, v111
	s_nop 0
	v_add_f32_e32 v14, v14, v108
	v_add_f32_e32 v14, v14, v109
	v_add_f32_e32 v14, v14, v110
	v_add_f32_e32 v14, v14, v111
	v_cvt_pk_f16_f32 v66, v108, v109
	v_cvt_pk_f16_f32 v67, v110, v111
	ds_write_b64 v8, v[66:67] offset:96
	v_sub_f32_e32 v112, v112, v13
	v_sub_f32_e32 v113, v113, v13
	v_sub_f32_e32 v114, v114, v13
	v_sub_f32_e32 v115, v115, v13
	v_mul_f32_e32 v112, 0x3fb8aa3b, v112
	v_mul_f32_e32 v113, 0x3fb8aa3b, v113
	v_mul_f32_e32 v114, 0x3fb8aa3b, v114
	v_mul_f32_e32 v115, 0x3fb8aa3b, v115
	v_exp_f32_e32 v112, v112
	v_exp_f32_e32 v113, v113
	v_exp_f32_e32 v114, v114
	v_exp_f32_e32 v115, v115
	s_nop 0
	v_add_f32_e32 v14, v14, v112
	v_add_f32_e32 v14, v14, v113
	v_add_f32_e32 v14, v14, v114
	v_add_f32_e32 v14, v14, v115
	v_cvt_pk_f16_f32 v64, v112, v113
	v_cvt_pk_f16_f32 v65, v114, v115
	ds_write_b64 v8, v[64:65] offset:128
	v_sub_f32_e32 v116, v116, v13
	v_sub_f32_e32 v117, v117, v13
	v_sub_f32_e32 v118, v118, v13
	v_sub_f32_e32 v119, v119, v13
	v_mul_f32_e32 v116, 0x3fb8aa3b, v116
	v_mul_f32_e32 v117, 0x3fb8aa3b, v117
	v_mul_f32_e32 v118, 0x3fb8aa3b, v118
	v_mul_f32_e32 v119, 0x3fb8aa3b, v119
	v_exp_f32_e32 v116, v116
	v_exp_f32_e32 v117, v117
	v_exp_f32_e32 v118, v118
	v_exp_f32_e32 v119, v119
	s_nop 0
	v_add_f32_e32 v14, v14, v116
	v_add_f32_e32 v14, v14, v117
	v_add_f32_e32 v14, v14, v118
	v_add_f32_e32 v14, v14, v119
	v_cvt_pk_f16_f32 v66, v116, v117
	v_cvt_pk_f16_f32 v67, v118, v119
	ds_write_b64 v8, v[66:67] offset:160
	v_sub_f32_e32 v120, v120, v13
	v_sub_f32_e32 v121, v121, v13
	v_sub_f32_e32 v122, v122, v13
	v_sub_f32_e32 v123, v123, v13
	v_mul_f32_e32 v120, 0x3fb8aa3b, v120
	v_mul_f32_e32 v121, 0x3fb8aa3b, v121
	v_mul_f32_e32 v122, 0x3fb8aa3b, v122
	v_mul_f32_e32 v123, 0x3fb8aa3b, v123
	v_exp_f32_e32 v120, v120
	v_exp_f32_e32 v121, v121
	v_exp_f32_e32 v122, v122
	v_exp_f32_e32 v123, v123
	s_nop 0
	v_add_f32_e32 v14, v14, v120
	v_add_f32_e32 v14, v14, v121
	v_add_f32_e32 v14, v14, v122
	v_add_f32_e32 v14, v14, v123
	v_cvt_pk_f16_f32 v64, v120, v121
	v_cvt_pk_f16_f32 v65, v122, v123
	ds_write_b64 v8, v[64:65] offset:192
	v_sub_f32_e32 v124, v124, v13
	v_sub_f32_e32 v125, v125, v13
	v_sub_f32_e32 v126, v126, v13
	v_sub_f32_e32 v127, v127, v13
	v_mul_f32_e32 v124, 0x3fb8aa3b, v124
	v_mul_f32_e32 v125, 0x3fb8aa3b, v125
	v_mul_f32_e32 v126, 0x3fb8aa3b, v126
	v_mul_f32_e32 v127, 0x3fb8aa3b, v127
	v_exp_f32_e32 v124, v124
	v_exp_f32_e32 v125, v125
	v_exp_f32_e32 v126, v126
	v_exp_f32_e32 v127, v127
	s_nop 0
	v_add_f32_e32 v14, v14, v124
	v_add_f32_e32 v14, v14, v125
	v_add_f32_e32 v14, v14, v126
	v_add_f32_e32 v14, v14, v127
	v_cvt_pk_f16_f32 v66, v124, v125
	v_cvt_pk_f16_f32 v67, v126, v127
	ds_write_b64 v8, v[66:67] offset:224
	v_sub_f32_e32 v128, v128, v13
	v_sub_f32_e32 v129, v129, v13
	v_sub_f32_e32 v130, v130, v13
	v_sub_f32_e32 v131, v131, v13
	v_mul_f32_e32 v128, 0x3fb8aa3b, v128
	v_mul_f32_e32 v129, 0x3fb8aa3b, v129
	v_mul_f32_e32 v130, 0x3fb8aa3b, v130
	v_mul_f32_e32 v131, 0x3fb8aa3b, v131
	v_exp_f32_e32 v128, v128
	v_exp_f32_e32 v129, v129
	v_exp_f32_e32 v130, v130
	v_exp_f32_e32 v131, v131
	s_nop 0
	v_add_f32_e32 v14, v14, v128
	v_add_f32_e32 v14, v14, v129
	v_add_f32_e32 v14, v14, v130
	v_add_f32_e32 v14, v14, v131
	v_cvt_pk_f16_f32 v64, v128, v129
	v_cvt_pk_f16_f32 v65, v130, v131
	ds_write_b64 v8, v[64:65] offset:256
	v_sub_f32_e32 v132, v132, v13
	v_sub_f32_e32 v133, v133, v13
	v_sub_f32_e32 v134, v134, v13
	v_sub_f32_e32 v135, v135, v13
	v_mul_f32_e32 v132, 0x3fb8aa3b, v132
	v_mul_f32_e32 v133, 0x3fb8aa3b, v133
	v_mul_f32_e32 v134, 0x3fb8aa3b, v134
	v_mul_f32_e32 v135, 0x3fb8aa3b, v135
	v_exp_f32_e32 v132, v132
	v_exp_f32_e32 v133, v133
	v_exp_f32_e32 v134, v134
	v_exp_f32_e32 v135, v135
	s_nop 0
	v_add_f32_e32 v14, v14, v132
	v_add_f32_e32 v14, v14, v133
	v_add_f32_e32 v14, v14, v134
	v_add_f32_e32 v14, v14, v135
	v_cvt_pk_f16_f32 v66, v132, v133
	v_cvt_pk_f16_f32 v67, v134, v135
	ds_write_b64 v8, v[66:67] offset:288
	v_sub_f32_e32 v136, v136, v13
	v_sub_f32_e32 v137, v137, v13
	v_sub_f32_e32 v138, v138, v13
	v_sub_f32_e32 v139, v139, v13
	v_mul_f32_e32 v136, 0x3fb8aa3b, v136
	v_mul_f32_e32 v137, 0x3fb8aa3b, v137
	v_mul_f32_e32 v138, 0x3fb8aa3b, v138
	v_mul_f32_e32 v139, 0x3fb8aa3b, v139
	v_exp_f32_e32 v136, v136
	v_exp_f32_e32 v137, v137
	v_exp_f32_e32 v138, v138
	v_exp_f32_e32 v139, v139
	s_nop 0
	v_add_f32_e32 v14, v14, v136
	v_add_f32_e32 v14, v14, v137
	v_add_f32_e32 v14, v14, v138
	v_add_f32_e32 v14, v14, v139
	v_cvt_pk_f16_f32 v64, v136, v137
	v_cvt_pk_f16_f32 v65, v138, v139
	ds_write_b64 v8, v[64:65] offset:320
	v_sub_f32_e32 v140, v140, v13
	v_sub_f32_e32 v141, v141, v13
	v_sub_f32_e32 v142, v142, v13
	v_sub_f32_e32 v143, v143, v13
	v_mul_f32_e32 v140, 0x3fb8aa3b, v140
	v_mul_f32_e32 v141, 0x3fb8aa3b, v141
	v_mul_f32_e32 v142, 0x3fb8aa3b, v142
	v_mul_f32_e32 v143, 0x3fb8aa3b, v143
	v_exp_f32_e32 v140, v140
	v_exp_f32_e32 v141, v141
	v_exp_f32_e32 v142, v142
	v_exp_f32_e32 v143, v143
	s_nop 0
	v_add_f32_e32 v14, v14, v140
	v_add_f32_e32 v14, v14, v141
	v_add_f32_e32 v14, v14, v142
	v_add_f32_e32 v14, v14, v143
	v_cvt_pk_f16_f32 v66, v140, v141
	v_cvt_pk_f16_f32 v67, v142, v143
; #define LAS __attribute__((address_space(3)))
; __device__ __forceinline__ void mem_attn_phase(int wv, const Args& A, LAS unsigned char* lds, int G) {
;     ...
;     for (int wu = blockIdx.x * 8 + w; wu < (MT / 16) * 4; wu += G * 8) {
;         const int blk = wu >> 3; const int h = blk & 3, tile = (blk >> 2) * 8 + (wu & 7); const size_t row0 = (size_t)tile * 16;
;         const h16* Kb; const h16* VTb;
;         if (row0 < NP) { const int b = (int)(row0 >> 14); Kb = (const h16*)(ws + WS_MK16) + (size_t)b * 256 * 512; VTb = (const h16*)(ws + WS_MVT) + (size_t)(b * 4 + h) * 32768; }
;         else { const int bs = (int)((row0 - NP) >> 6); Kb = (const h16*)(ws + WS_CMK) + (size_t)bs * 256 * 512; VTb = (const h16*)(ws + WS_CMVT) + (size_t)(bs * 4 + h) * 32768; }
;         h16x8 qf[4];
; #pragma unroll
;         for (int ks = 0; ks < 4; ++ks) qf[ks] = __builtin_bit_cast(h16x8, *(const u32x4*)(MQ + (row0 + fr) * 512 + h * 128 + ks * 32 + fq * 8));
;     ...
;         sm += __shfl_xor(sm, 16); sm += __shfl_xor(sm, 32);
;         const float inv = 1.f / sm;
; #pragma unroll
;         for (int db = 0; db < 8; ++db) { f32x4 o = {0.f, 0.f, 0.f, 0.f};
; #pragma unroll
;             for (int ks = 0; ks < 8; ++ks) { const h16x8 vf = __builtin_bit_cast(h16x8, *(const u32x4*)(VTb + (size_t)(db * 16 + fr) * 256 + ks * 32 + fq * 8));
;                 const h16x8 pf = *(const LAS h16x8*)(Pw + fr * 264 + ks * 32 + fq * 8); o = __builtin_amdgcn_mfma_f32_16x16x32_f16(vf, pf, o, 0, 0, 0); }
	ds_write_b64 v8, v[66:67] offset:352
	v_sub_f32_e32 v144, v144, v13
	v_sub_f32_e32 v145, v145, v13
	v_sub_f32_e32 v146, v146, v13
	v_sub_f32_e32 v147, v147, v13
	v_mul_f32_e32 v144, 0x3fb8aa3b, v144
	v_mul_f32_e32 v145, 0x3fb8aa3b, v145
	v_mul_f32_e32 v146, 0x3fb8aa3b, v146
	v_mul_f32_e32 v147, 0x3fb8aa3b, v147
	v_exp_f32_e32 v144, v144
	v_exp_f32_e32 v145, v145
	v_exp_f32_e32 v146, v146
	v_exp_f32_e32 v147, v147
	s_nop 0
	v_add_f32_e32 v14, v14, v144
	v_add_f32_e32 v14, v14, v145
	v_add_f32_e32 v14, v14, v146
	v_add_f32_e32 v14, v14, v147
	v_cvt_pk_f16_f32 v64, v144, v145
	v_cvt_pk_f16_f32 v65, v146, v147
	ds_write_b64 v8, v[64:65] offset:384
	v_sub_f32_e32 v148, v148, v13
	v_sub_f32_e32 v149, v149, v13
	v_sub_f32_e32 v150, v150, v13
	v_sub_f32_e32 v151, v151, v13
	v_mul_f32_e32 v148, 0x3fb8aa3b, v148
	v_mul_f32_e32 v149, 0x3fb8aa3b, v149
	v_mul_f32_e32 v150, 0x3fb8aa3b, v150
	v_mul_f32_e32 v151, 0x3fb8aa3b, v151
	v_exp_f32_e32 v148, v148
	v_exp_f32_e32 v149, v149
	v_exp_f32_e32 v150, v150
	v_exp_f32_e32 v151, v151
	s_nop 0
	v_add_f32_e32 v14, v14, v148
	v_add_f32_e32 v14, v14, v149
	v_add_f32_e32 v14, v14, v150
	v_add_f32_e32 v14, v14, v151
	v_cvt_pk_f16_f32 v66, v148, v149
	v_cvt_pk_f16_f32 v67, v150, v151
	ds_write_b64 v8, v[66:67] offset:416
	v_sub_f32_e32 v152, v152, v13
	v_sub_f32_e32 v153, v153, v13
	v_sub_f32_e32 v154, v154, v13
	v_sub_f32_e32 v155, v155, v13
	v_mul_f32_e32 v152, 0x3fb8aa3b, v152
	v_mul_f32_e32 v153, 0x3fb8aa3b, v153
	v_mul_f32_e32 v154, 0x3fb8aa3b, v154
	v_mul_f32_e32 v155, 0x3fb8aa3b, v155
	v_exp_f32_e32 v152, v152
	v_exp_f32_e32 v153, v153
	v_exp_f32_e32 v154, v154
	v_exp_f32_e32 v155, v155
	s_nop 0
	v_add_f32_e32 v14, v14, v152
	v_add_f32_e32 v14, v14, v153
	v_add_f32_e32 v14, v14, v154
	v_add_f32_e32 v14, v14, v155
	v_cvt_pk_f16_f32 v64, v152, v153
	v_cvt_pk_f16_f32 v65, v154, v155
	ds_write_b64 v8, v[64:65] offset:448
	v_sub_f32_e32 v156, v156, v13
	v_sub_f32_e32 v157, v157, v13
	v_sub_f32_e32 v158, v158, v13
	v_sub_f32_e32 v159, v159, v13
	v_mul_f32_e32 v156, 0x3fb8aa3b, v156
	v_mul_f32_e32 v157, 0x3fb8aa3b, v157
	v_mul_f32_e32 v158, 0x3fb8aa3b, v158
	v_mul_f32_e32 v159, 0x3fb8aa3b, v159
	v_exp_f32_e32 v156, v156
	v_exp_f32_e32 v157, v157
	v_exp_f32_e32 v158, v158
	v_exp_f32_e32 v159, v159
	s_nop 0
	v_add_f32_e32 v14, v14, v156
	v_add_f32_e32 v14, v14, v157
	v_add_f32_e32 v14, v14, v158
	v_add_f32_e32 v14, v14, v159
	v_cvt_pk_f16_f32 v66, v156, v157
	v_cvt_pk_f16_f32 v67, v158, v159
	ds_write_b64 v8, v[66:67] offset:480
	ds_bpermute_b32 v68, v11, v14
	s_waitcnt lgkmcnt(0)
	v_add_f32_e32 v14, v14, v68
	ds_bpermute_b32 v68, v12, v14
	s_waitcnt lgkmcnt(0)
	v_add_f32_e32 v14, v14, v68
	v_div_scale_f32 v64, s[34:35], v14, v14, 1.0
	v_div_scale_f32 v67, vcc, 1.0, v14, 1.0
	v_rcp_f32_e32 v65, v64
	s_nop 0
	v_fma_f32 v66, -v64, v65, 1.0
	v_fmac_f32_e32 v65, v66, v65
	v_mul_f32_e32 v68, v67, v65
	v_fma_f32 v69, -v64, v68, v67
	v_fmac_f32_e32 v68, v69, v65
	v_fma_f32 v64, -v64, v68, v67
	v_div_fmas_f32 v70, v64, v65, v68
	v_div_fixup_f32 v15, v70, v14, 1.0
	ds_read_b128 v[96:99], v9
	ds_read_b128 v[100:103], v9 offset:64
	ds_read_b128 v[104:107], v9 offset:128
	ds_read_b128 v[108:111], v9 offset:192
	ds_read_b128 v[112:115], v9 offset:256
	ds_read_b128 v[116:119], v9 offset:320
	ds_read_b128 v[120:123], v9 offset:384
	ds_read_b128 v[124:127], v9 offset:448
	s_barrier
	s_waitcnt vmcnt(0)
	ds_write_b128 v6, v[182:185]
	ds_write_b128 v6, v[186:189] offset:1024
	ds_write_b128 v6, v[190:193] offset:2048
	ds_write_b128 v6, v[194:197] offset:3072
	ds_write_b128 v6, v[198:201] offset:4096
	ds_write_b128 v6, v[202:205] offset:5120
	ds_write_b128 v6, v[206:209] offset:6144
	ds_write_b128 v6, v[210:213] offset:7168
	s_waitcnt lgkmcnt(0)
	s_barrier
	s_add_i32 s77, s71, 1
	s_cmp_lt_u32 s77, 4
	s_cbranch_scc0 .Lma_nopf
	s_lshl_b32 s72, s77, 8
	s_add_i32 s73, s2, s72
	s_and_b32 s74, s73, 3
	s_lshr_b32 s75, s73, 2
	s_lshl_b32 s75, s75, 3
	s_add_i32 s75, s75, s70
	s_lshr_b32 s76, s75, 10
	s_lshl_b32 s32, s76, 18
	s_lshl_b32 s33, s74, 8
	s_add_i32 s32, s32, s33
	s_lshl_b32 s33, s70, 15
	s_add_i32 s32, s32, s33
	s_add_u32 s78, s44, 0x3cc4d000
	s_addc_u32 s79, s45, 0
	s_add_u32 s78, s78, s32
	s_addc_u32 s79, s79, 0
	s_add_u32 s88, s78, 0x4000
	s_addc_u32 s89, s79, 0
	s_lshl_b32 s32, s76, 2
	s_add_i32 s32, s32, s74
	s_lshl_b32 s32, s32, 16
	s_lshl_b32 s33, s70, 13
	s_add_i32 s32, s32, s33
	s_add_u32 s90, s44, 0x3cccd000
	s_addc_u32 s91, s45, 0
	s_add_u32 s90, s90, s32
	s_addc_u32 s91, s91, 0
	s_lshl_b32 s32, s75, 14
	s_lshl_b32 s33, s74, 8
	s_add_i32 s32, s32, s33
	s_add_u32 s92, s44, 0x324c1000
	s_addc_u32 s93, s45, 0
	s_add_u32 s92, s92, s32
	s_addc_u32 s93, s93, 0
	s_add_u32 s36, s44, 0x34541000
	s_addc_u32 s37, s45, 0
	s_add_u32 s36, s36, s32
	s_addc_u32 s37, s37, 0
	global_load_dwordx4 v[140:143], v4, s[78:79]
	global_load_dwordx4 v[144:147], v4, s[78:79] offset:64
	global_load_dwordx4 v[148:151], v4, s[78:79] offset:128
	global_load_dwordx4 v[152:155], v4, s[78:79] offset:192
	global_load_dwordx4 v[156:159], v4, s[88:89]
	global_load_dwordx4 v[160:163], v4, s[88:89] offset:64
	global_load_dwordx4 v[164:167], v4, s[88:89] offset:128
	global_load_dwordx4 v[214:217], v4, s[88:89] offset:192
	global_load_dwordx4 v[16:19], v4, s[92:93]
	global_load_dwordx4 v[20:23], v4, s[92:93] offset:64
	global_load_dwordx4 v[24:27], v4, s[92:93] offset:128
	global_load_dwordx4 v[28:31], v4, s[92:93] offset:192
	global_load_dwordx4 v[182:185], v5, s[90:91]
	global_load_dwordx4 v[186:189], v5, s[90:91] offset:64
	global_load_dwordx4 v[190:193], v5, s[90:91] offset:128
	global_load_dwordx4 v[194:197], v5, s[90:91] offset:192
	global_load_dwordx4 v[198:201], v5, s[90:91] offset:256
	global_load_dwordx4 v[202:205], v5, s[90:91] offset:320
	global_load_dwordx4 v[206:209], v5, s[90:91] offset:384
	global_load_dwordx4 v[210:213], v5, s[90:91] offset:448
